# P13 sample-row skinny GEMM: unrolled K-loop re-pipelined with 4-chunk load ring (counted vmcnt) instead of vmcnt(1-2) after each load
# baseline (speedup 1.0000x reference)
;     ...
;     for (int item = bx; item < nct * nrh * (8 / RB); item += G) {
;         const int ct = item % nct, rs = item / nct, row0 = rs * RB * 16, rh = row0 >> 7, rin = row0 & 127;
;         f32x4 acc[RB];
; #pragma unroll
;         for (int rb = 0; rb < RB; ++rb) acc[rb] = (f32x4){0.f, 0.f, 0.f, 0.f};
;         const bf16_t* bp = Wt + (size_t)(ct * 16 + fr) * ldb + wave * kw + fq * 8;
;         const bf16_t* ap = A + (size_t)(row0 + fr) * lda + wave * kw + fq * 8;
;         bf16x8 b0 = *(const bf16x8*)(bp), b1 = *(const bf16x8*)(bp + 32), a0[RB], a1[RB];
; #pragma unroll
;         for (int rb = 0; rb < RB; ++rb) { a0[rb] = *(const bf16x8*)(ap + (size_t)rb * 16 * lda); a1[rb] = *(const bf16x8*)(ap + (size_t)rb * 16 * lda + 32); }
;         for (int k = 0; k < kw; k += 64) {
;             bf16x8 nb0 = b0, nb1 = b1, na0[RB], na1[RB];
; #pragma unroll
;             for (int rb = 0; rb < RB; ++rb) { na0[rb] = a0[rb]; na1[rb] = a1[rb]; }
;             if (k + 64 < kw) {
;                 nb0 = *(const bf16x8*)(bp + k + 64); nb1 = *(const bf16x8*)(bp + k + 96);
; #pragma unroll
;                 for (int rb = 0; rb < RB; ++rb) { na0[rb] = *(const bf16x8*)(ap + (size_t)rb * 16 * lda + k + 64); na1[rb] = *(const bf16x8*)(ap + (size_t)rb * 16 * lda + k + 96); }
;             }
; #pragma unroll
;             for (int rb = 0; rb < RB; ++rb) acc[rb] = __builtin_amdgcn_mfma_f32_16x16x32_bf16(a0[rb], b0, acc[rb], 0, 0, 0);
; #pragma unroll
;             for (int rb = 0; rb < RB; ++rb) acc[rb] = __builtin_amdgcn_mfma_f32_16x16x32_bf16(a1[rb], b1, acc[rb], 0, 0, 0);
;             b0 = nb0; b1 = nb1;
; #pragma unroll
;             for (int rb = 0; rb < RB; ++rb) { a0[rb] = na0[rb]; a1[rb] = na1[rb]; }
;         }
.LBB0_872:
	s_ashr_i32 s0, s18, 31
	s_lshr_b32 s0, s0, 25
	s_add_i32 s0, s18, s0
	s_ashr_i32 s19, s0, 7
	s_lshl_b32 s20, s19, 6
	s_mul_i32 s21, s19, 0xff500000
	v_or_b32_e32 v0, s20, v196
	v_add_u32_e32 v8, s21, v19
	v_mad_i64_i32 v[6:7], s[0:1], v0, s14, v[4:5]
	v_ashrrev_i32_e32 v9, 31, v8
	v_lshl_add_u64 v[12:13], v[8:9], 1, v[2:3]
	v_add_co_u32_e64 v8, s[0:1], s15, v6
	s_nop 1
	v_addc_co_u32_e64 v9, s[0:1], 0, v7, s[0:1]
	v_add_co_u32_e64 v10, s[0:1], s16, v6
	s_nop 1
	v_addc_co_u32_e64 v11, s[0:1], 0, v7, s[0:1]
	v_add_co_u32_e64 v14, s[0:1], s17, v6
	s_nop 1
	v_addc_co_u32_e64 v15, s[0:1], 0, v7, s[0:1]
	global_load_dwordx4 v[74:77], v[12:13], off
	global_load_dwordx4 v[42:45], v[6:7], off
	global_load_dwordx4 v[50:53], v[8:9], off
	global_load_dwordx4 v[58:61], v[10:11], off
	global_load_dwordx4 v[66:69], v[14:15], off
	global_load_dwordx4 v[78:81], v[12:13], off offset:64
	global_load_dwordx4 v[46:49], v[6:7], off offset:64
	global_load_dwordx4 v[54:57], v[8:9], off offset:64
	global_load_dwordx4 v[62:65], v[10:11], off offset:64
	global_load_dwordx4 v[70:73], v[14:15], off offset:64
	global_load_dwordx4 v[114:117], v[12:13], off offset:128
	global_load_dwordx4 v[82:85], v[6:7], off offset:128
	global_load_dwordx4 v[90:93], v[8:9], off offset:128
	global_load_dwordx4 v[98:101], v[10:11], off offset:128
	global_load_dwordx4 v[106:109], v[14:15], off offset:128
	global_load_dwordx4 v[118:121], v[12:13], off offset:192
	global_load_dwordx4 v[86:89], v[6:7], off offset:192
	global_load_dwordx4 v[94:97], v[8:9], off offset:192
	global_load_dwordx4 v[102:105], v[10:11], off offset:192
	global_load_dwordx4 v[110:113], v[14:15], off offset:192
	global_load_dwordx4 v[154:157], v[12:13], off offset:256
	global_load_dwordx4 v[122:125], v[6:7], off offset:256
	global_load_dwordx4 v[130:133], v[8:9], off offset:256
	global_load_dwordx4 v[138:141], v[10:11], off offset:256
	global_load_dwordx4 v[146:149], v[14:15], off offset:256
	global_load_dwordx4 v[158:161], v[12:13], off offset:320
	global_load_dwordx4 v[126:129], v[6:7], off offset:320
	global_load_dwordx4 v[134:137], v[8:9], off offset:320
	global_load_dwordx4 v[142:145], v[10:11], off offset:320
	global_load_dwordx4 v[150:153], v[14:15], off offset:320
	global_load_dwordx4 v[202:205], v[12:13], off offset:384
	global_load_dwordx4 v[162:165], v[6:7], off offset:384
	global_load_dwordx4 v[170:173], v[8:9], off offset:384
	global_load_dwordx4 v[178:181], v[10:11], off offset:384
	global_load_dwordx4 v[186:189], v[14:15], off offset:384
	global_load_dwordx4 v[210:213], v[12:13], off offset:448
	global_load_dwordx4 v[166:169], v[6:7], off offset:448
	global_load_dwordx4 v[174:177], v[8:9], off offset:448
	global_load_dwordx4 v[182:185], v[10:11], off offset:448
	global_load_dwordx4 v[198:201], v[14:15], off offset:448
	s_waitcnt vmcnt(30)
	v_mfma_f32_16x16x32_bf16 v[26:29], v[42:45], v[74:77], 0
	v_mfma_f32_16x16x32_bf16 v[30:33], v[50:53], v[74:77], 0
	v_mfma_f32_16x16x32_bf16 v[34:37], v[58:61], v[74:77], 0
	v_mfma_f32_16x16x32_bf16 v[38:41], v[66:69], v[74:77], 0
	v_mfma_f32_16x16x32_bf16 v[26:29], v[46:49], v[78:81], v[26:29]
	v_mfma_f32_16x16x32_bf16 v[30:33], v[54:57], v[78:81], v[30:33]
	v_mfma_f32_16x16x32_bf16 v[34:37], v[62:65], v[78:81], v[34:37]
	v_mfma_f32_16x16x32_bf16 v[38:41], v[70:73], v[78:81], v[38:41]
	global_load_dwordx4 v[74:77], v[12:13], off offset:512
	global_load_dwordx4 v[42:45], v[6:7], off offset:512
	global_load_dwordx4 v[50:53], v[8:9], off offset:512
	global_load_dwordx4 v[58:61], v[10:11], off offset:512
	global_load_dwordx4 v[66:69], v[14:15], off offset:512
	global_load_dwordx4 v[78:81], v[12:13], off offset:576
	global_load_dwordx4 v[46:49], v[6:7], off offset:576
	global_load_dwordx4 v[54:57], v[8:9], off offset:576
	global_load_dwordx4 v[62:65], v[10:11], off offset:576
	global_load_dwordx4 v[70:73], v[14:15], off offset:576
	s_waitcnt vmcnt(30)
	v_mfma_f32_16x16x32_bf16 v[26:29], v[82:85], v[114:117], v[26:29]
	v_mfma_f32_16x16x32_bf16 v[30:33], v[90:93], v[114:117], v[30:33]
	v_mfma_f32_16x16x32_bf16 v[34:37], v[98:101], v[114:117], v[34:37]
	v_mfma_f32_16x16x32_bf16 v[38:41], v[106:109], v[114:117], v[38:41]
	v_mfma_f32_16x16x32_bf16 v[26:29], v[86:89], v[118:121], v[26:29]
	v_mfma_f32_16x16x32_bf16 v[30:33], v[94:97], v[118:121], v[30:33]
	v_mfma_f32_16x16x32_bf16 v[34:37], v[102:105], v[118:121], v[34:37]
	v_mfma_f32_16x16x32_bf16 v[38:41], v[110:113], v[118:121], v[38:41]
	global_load_dwordx4 v[114:117], v[12:13], off offset:640
	global_load_dwordx4 v[82:85], v[6:7], off offset:640
	global_load_dwordx4 v[90:93], v[8:9], off offset:640
	global_load_dwordx4 v[98:101], v[10:11], off offset:640
	global_load_dwordx4 v[106:109], v[14:15], off offset:640
	global_load_dwordx4 v[118:121], v[12:13], off offset:704
	global_load_dwordx4 v[86:89], v[6:7], off offset:704
	global_load_dwordx4 v[94:97], v[8:9], off offset:704
	global_load_dwordx4 v[102:105], v[10:11], off offset:704
	global_load_dwordx4 v[110:113], v[14:15], off offset:704
	s_waitcnt vmcnt(30)
	v_mfma_f32_16x16x32_bf16 v[26:29], v[122:125], v[154:157], v[26:29]
	v_mfma_f32_16x16x32_bf16 v[30:33], v[130:133], v[154:157], v[30:33]
	v_mfma_f32_16x16x32_bf16 v[34:37], v[138:141], v[154:157], v[34:37]
	v_mfma_f32_16x16x32_bf16 v[38:41], v[146:149], v[154:157], v[38:41]
	v_mfma_f32_16x16x32_bf16 v[26:29], v[126:129], v[158:161], v[26:29]
	v_mfma_f32_16x16x32_bf16 v[30:33], v[134:137], v[158:161], v[30:33]
	v_mfma_f32_16x16x32_bf16 v[34:37], v[142:145], v[158:161], v[34:37]
	v_mfma_f32_16x16x32_bf16 v[38:41], v[150:153], v[158:161], v[38:41]
	global_load_dwordx4 v[154:157], v[12:13], off offset:768
	global_load_dwordx4 v[122:125], v[6:7], off offset:768
	global_load_dwordx4 v[130:133], v[8:9], off offset:768
	global_load_dwordx4 v[138:141], v[10:11], off offset:768
	global_load_dwordx4 v[146:149], v[14:15], off offset:768
	global_load_dwordx4 v[158:161], v[12:13], off offset:832
	global_load_dwordx4 v[126:129], v[6:7], off offset:832
	global_load_dwordx4 v[134:137], v[8:9], off offset:832
	global_load_dwordx4 v[142:145], v[10:11], off offset:832
	global_load_dwordx4 v[150:153], v[14:15], off offset:832
	s_waitcnt vmcnt(30)
;     ...
;         for (int k = 0; k < kw; k += 64) {
;             bf16x8 nb0 = b0, nb1 = b1, na0[RB], na1[RB];
; #pragma unroll
;             for (int rb = 0; rb < RB; ++rb) { na0[rb] = a0[rb]; na1[rb] = a1[rb]; }
;             if (k + 64 < kw) {
;                 nb0 = *(const bf16x8*)(bp + k + 64); nb1 = *(const bf16x8*)(bp + k + 96);
; #pragma unroll
;                 for (int rb = 0; rb < RB; ++rb) { na0[rb] = *(const bf16x8*)(ap + (size_t)rb * 16 * lda + k + 64); na1[rb] = *(const bf16x8*)(ap + (size_t)rb * 16 * lda + k + 96); }
;             }
; #pragma unroll
;             for (int rb = 0; rb < RB; ++rb) acc[rb] = __builtin_amdgcn_mfma_f32_16x16x32_bf16(a0[rb], b0, acc[rb], 0, 0, 0);
; #pragma unroll
;             for (int rb = 0; rb < RB; ++rb) acc[rb] = __builtin_amdgcn_mfma_f32_16x16x32_bf16(a1[rb], b1, acc[rb], 0, 0, 0);
;             b0 = nb0; b1 = nb1;
; #pragma unroll
;             for (int rb = 0; rb < RB; ++rb) { a0[rb] = na0[rb]; a1[rb] = na1[rb]; }
;         }
	v_mfma_f32_16x16x32_bf16 v[26:29], v[162:165], v[202:205], v[26:29]
	v_mfma_f32_16x16x32_bf16 v[30:33], v[170:173], v[202:205], v[30:33]
	v_mfma_f32_16x16x32_bf16 v[34:37], v[178:181], v[202:205], v[34:37]
	v_mfma_f32_16x16x32_bf16 v[38:41], v[186:189], v[202:205], v[38:41]
	v_mfma_f32_16x16x32_bf16 v[26:29], v[166:169], v[210:213], v[26:29]
	v_mfma_f32_16x16x32_bf16 v[30:33], v[174:177], v[210:213], v[30:33]
	v_mfma_f32_16x16x32_bf16 v[34:37], v[182:185], v[210:213], v[34:37]
	v_mfma_f32_16x16x32_bf16 v[38:41], v[198:201], v[210:213], v[38:41]
	global_load_dwordx4 v[202:205], v[12:13], off offset:896
	global_load_dwordx4 v[162:165], v[6:7], off offset:896
	global_load_dwordx4 v[170:173], v[8:9], off offset:896
	global_load_dwordx4 v[178:181], v[10:11], off offset:896
	global_load_dwordx4 v[186:189], v[14:15], off offset:896
	global_load_dwordx4 v[210:213], v[12:13], off offset:960
	global_load_dwordx4 v[166:169], v[6:7], off offset:960
	global_load_dwordx4 v[174:177], v[8:9], off offset:960
	global_load_dwordx4 v[182:185], v[10:11], off offset:960
	global_load_dwordx4 v[198:201], v[14:15], off offset:960
	s_waitcnt vmcnt(30)
	v_mfma_f32_16x16x32_bf16 v[26:29], v[42:45], v[74:77], v[26:29]
	v_mfma_f32_16x16x32_bf16 v[30:33], v[50:53], v[74:77], v[30:33]
	v_mfma_f32_16x16x32_bf16 v[34:37], v[58:61], v[74:77], v[34:37]
	v_mfma_f32_16x16x32_bf16 v[38:41], v[66:69], v[74:77], v[38:41]
	v_mfma_f32_16x16x32_bf16 v[26:29], v[46:49], v[78:81], v[26:29]
	v_mfma_f32_16x16x32_bf16 v[30:33], v[54:57], v[78:81], v[30:33]
	v_mfma_f32_16x16x32_bf16 v[34:37], v[62:65], v[78:81], v[34:37]
	v_mfma_f32_16x16x32_bf16 v[38:41], v[70:73], v[78:81], v[38:41]
	global_load_dwordx4 v[74:77], v[12:13], off offset:1024
	global_load_dwordx4 v[42:45], v[6:7], off offset:1024
	global_load_dwordx4 v[50:53], v[8:9], off offset:1024
	global_load_dwordx4 v[58:61], v[10:11], off offset:1024
	global_load_dwordx4 v[66:69], v[14:15], off offset:1024
	global_load_dwordx4 v[78:81], v[12:13], off offset:1088
	global_load_dwordx4 v[46:49], v[6:7], off offset:1088
	global_load_dwordx4 v[54:57], v[8:9], off offset:1088
	global_load_dwordx4 v[62:65], v[10:11], off offset:1088
	global_load_dwordx4 v[70:73], v[14:15], off offset:1088
	s_waitcnt vmcnt(30)
	v_mfma_f32_16x16x32_bf16 v[26:29], v[82:85], v[114:117], v[26:29]
	v_mfma_f32_16x16x32_bf16 v[30:33], v[90:93], v[114:117], v[30:33]
	v_mfma_f32_16x16x32_bf16 v[34:37], v[98:101], v[114:117], v[34:37]
	v_mfma_f32_16x16x32_bf16 v[38:41], v[106:109], v[114:117], v[38:41]
	v_mfma_f32_16x16x32_bf16 v[26:29], v[86:89], v[118:121], v[26:29]
	v_mfma_f32_16x16x32_bf16 v[30:33], v[94:97], v[118:121], v[30:33]
	v_mfma_f32_16x16x32_bf16 v[34:37], v[102:105], v[118:121], v[34:37]
	v_mfma_f32_16x16x32_bf16 v[38:41], v[110:113], v[118:121], v[38:41]
	global_load_dwordx4 v[114:117], v[12:13], off offset:1152
	global_load_dwordx4 v[82:85], v[6:7], off offset:1152
	global_load_dwordx4 v[90:93], v[8:9], off offset:1152
	global_load_dwordx4 v[98:101], v[10:11], off offset:1152
	global_load_dwordx4 v[106:109], v[14:15], off offset:1152
	global_load_dwordx4 v[118:121], v[12:13], off offset:1216
	global_load_dwordx4 v[86:89], v[6:7], off offset:1216
	global_load_dwordx4 v[94:97], v[8:9], off offset:1216
	global_load_dwordx4 v[102:105], v[10:11], off offset:1216
	global_load_dwordx4 v[110:113], v[14:15], off offset:1216
	s_waitcnt vmcnt(30)
	v_mfma_f32_16x16x32_bf16 v[26:29], v[122:125], v[154:157], v[26:29]
	v_mfma_f32_16x16x32_bf16 v[30:33], v[130:133], v[154:157], v[30:33]
	v_mfma_f32_16x16x32_bf16 v[34:37], v[138:141], v[154:157], v[34:37]
	v_mfma_f32_16x16x32_bf16 v[38:41], v[146:149], v[154:157], v[38:41]
	v_mfma_f32_16x16x32_bf16 v[26:29], v[126:129], v[158:161], v[26:29]
	v_mfma_f32_16x16x32_bf16 v[30:33], v[134:137], v[158:161], v[30:33]
	v_mfma_f32_16x16x32_bf16 v[34:37], v[142:145], v[158:161], v[34:37]
	v_mfma_f32_16x16x32_bf16 v[38:41], v[150:153], v[158:161], v[38:41]
	global_load_dwordx4 v[154:157], v[12:13], off offset:1280
	global_load_dwordx4 v[122:125], v[6:7], off offset:1280
	global_load_dwordx4 v[130:133], v[8:9], off offset:1280
	global_load_dwordx4 v[138:141], v[10:11], off offset:1280
	global_load_dwordx4 v[146:149], v[14:15], off offset:1280
	global_load_dwordx4 v[158:161], v[12:13], off offset:1344
	global_load_dwordx4 v[126:129], v[6:7], off offset:1344
	global_load_dwordx4 v[134:137], v[8:9], off offset:1344
	global_load_dwordx4 v[142:145], v[10:11], off offset:1344
	global_load_dwordx4 v[150:153], v[14:15], off offset:1344
	s_waitcnt vmcnt(30)
; #define LAS __attribute__((address_space(3)))
;     ...
;             for (int rb = 0; rb < RB; ++rb) acc[rb] = __builtin_amdgcn_mfma_f32_16x16x32_bf16(a0[rb], b0, acc[rb], 0, 0, 0);
; #pragma unroll
;             for (int rb = 0; rb < RB; ++rb) acc[rb] = __builtin_amdgcn_mfma_f32_16x16x32_bf16(a1[rb], b1, acc[rb], 0, 0, 0);
;             b0 = nb0; b1 = nb1;
; #pragma unroll
;             for (int rb = 0; rb < RB; ++rb) { a0[rb] = na0[rb]; a1[rb] = na1[rb]; }
;         }
; #pragma unroll
;         for (int rb = 0; rb < RB; ++rb)
; #pragma unroll
;             for (int j = 0; j < 4; ++j) red[(wave * (RB * 16) + rb * 16 + 4 * fq + j) * 16 + fr] = acc[rb][j];
;         __syncthreads();
;         if (tid < RB * 64) { const int e = tid * 4, row = e >> 4, col = e & 15;
;             f32x4 v = *(const LAS f32x4*)(red + row * 16 + col);
; #pragma unroll
;             for (int w = 1; w < 8; ++w) v += *(const LAS f32x4*)(red + (w * (RB * 16) + row) * 16 + col);
;             E(rin + row, rh, ct * 16 + col, v); }
;         __syncthreads();
	v_mfma_f32_16x16x32_bf16 v[26:29], v[162:165], v[202:205], v[26:29]
	v_mfma_f32_16x16x32_bf16 v[30:33], v[170:173], v[202:205], v[30:33]
	v_mfma_f32_16x16x32_bf16 v[34:37], v[178:181], v[202:205], v[34:37]
	v_mfma_f32_16x16x32_bf16 v[38:41], v[186:189], v[202:205], v[38:41]
	v_mfma_f32_16x16x32_bf16 v[26:29], v[166:169], v[210:213], v[26:29]
	v_mfma_f32_16x16x32_bf16 v[30:33], v[174:177], v[210:213], v[30:33]
	v_mfma_f32_16x16x32_bf16 v[34:37], v[182:185], v[210:213], v[34:37]
	v_mfma_f32_16x16x32_bf16 v[38:41], v[198:201], v[210:213], v[38:41]
	s_waitcnt vmcnt(20)
	v_mfma_f32_16x16x32_bf16 v[26:29], v[42:45], v[74:77], v[26:29]
	v_mfma_f32_16x16x32_bf16 v[30:33], v[50:53], v[74:77], v[30:33]
	v_mfma_f32_16x16x32_bf16 v[34:37], v[58:61], v[74:77], v[34:37]
	v_mfma_f32_16x16x32_bf16 v[38:41], v[66:69], v[74:77], v[38:41]
	v_mfma_f32_16x16x32_bf16 v[26:29], v[46:49], v[78:81], v[26:29]
	v_mfma_f32_16x16x32_bf16 v[30:33], v[54:57], v[78:81], v[30:33]
	v_mfma_f32_16x16x32_bf16 v[34:37], v[62:65], v[78:81], v[34:37]
	v_mfma_f32_16x16x32_bf16 v[38:41], v[70:73], v[78:81], v[38:41]
	s_waitcnt vmcnt(10)
	v_mfma_f32_16x16x32_bf16 v[26:29], v[82:85], v[114:117], v[26:29]
	v_mfma_f32_16x16x32_bf16 v[30:33], v[90:93], v[114:117], v[30:33]
	v_mfma_f32_16x16x32_bf16 v[34:37], v[98:101], v[114:117], v[34:37]
	v_mfma_f32_16x16x32_bf16 v[38:41], v[106:109], v[114:117], v[38:41]
	v_mfma_f32_16x16x32_bf16 v[26:29], v[86:89], v[118:121], v[26:29]
	v_mfma_f32_16x16x32_bf16 v[30:33], v[94:97], v[118:121], v[30:33]
	v_mfma_f32_16x16x32_bf16 v[34:37], v[102:105], v[118:121], v[34:37]
	v_mfma_f32_16x16x32_bf16 v[38:41], v[110:113], v[118:121], v[38:41]
	s_waitcnt vmcnt(0)
	v_mfma_f32_16x16x32_bf16 v[26:29], v[122:125], v[154:157], v[26:29]
	v_mfma_f32_16x16x32_bf16 v[30:33], v[130:133], v[154:157], v[30:33]
	v_mfma_f32_16x16x32_bf16 v[34:37], v[138:141], v[154:157], v[34:37]
	v_mfma_f32_16x16x32_bf16 v[38:41], v[146:149], v[154:157], v[38:41]
	v_mfma_f32_16x16x32_bf16 v[26:29], v[126:129], v[158:161], v[26:29]
	v_mfma_f32_16x16x32_bf16 v[30:33], v[134:137], v[158:161], v[30:33]
	v_mfma_f32_16x16x32_bf16 v[34:37], v[142:145], v[158:161], v[34:37]
	v_mfma_f32_16x16x32_bf16 v[38:41], v[150:153], v[158:161], v[38:41]
	s_nop 7
	s_nop 1
	ds_write2_b32 v21, v26, v27 offset1:16
	ds_write2_b32 v21, v28, v29 offset0:32 offset1:48
	ds_write2_b32 v22, v30, v31 offset1:16
	ds_write2_b32 v22, v32, v33 offset0:32 offset1:48
	ds_write2_b32 v23, v34, v35 offset1:16
	ds_write2_b32 v23, v36, v37 offset0:32 offset1:48
	ds_write2_b32 v24, v38, v39 offset1:16
	ds_write2_b32 v24, v40, v41 offset0:32 offset1:48
	s_waitcnt lgkmcnt(0)
	s_barrier
	s_and_saveexec_b64 s[0:1], vcc
	s_cbranch_execz .LBB0_871
	s_lshl_b32 s19, s19, 11
	v_and_or_b32 v0, s20, 64, v208
	v_subrev_u32_e32 v6, s19, v20
	v_lshlrev_b32_e32 v0, 13, v0
	v_ashrrev_i32_e32 v7, 31, v6
	v_lshl_add_u64 v[8:9], s[4:5], 0, v[0:1]
	v_lshlrev_b64 v[14:15], 2, v[6:7]
	v_lshl_add_u64 v[6:7], v[8:9], 0, v[14:15]
	global_load_dwordx4 v[6:9], v[6:7], off
	ds_read_b128 v[10:13], v18
	ds_read_b128 v[26:29], v18 offset:4096
	ds_read_b128 v[30:33], v18 offset:8192
	ds_read_b128 v[34:37], v18 offset:12288
	ds_read_b128 v[38:41], v18 offset:16384
	ds_read_b128 v[42:45], v18 offset:20480
	ds_read_b128 v[46:49], v18 offset:24576
	ds_read_b128 v[50:53], v18 offset:28672
	s_waitcnt lgkmcnt(6)
	v_pk_add_f32 v[12:13], v[12:13], v[28:29]
	v_pk_add_f32 v[10:11], v[10:11], v[26:27]
	s_waitcnt lgkmcnt(5)
	v_pk_add_f32 v[12:13], v[12:13], v[32:33]
	v_pk_add_f32 v[10:11], v[10:11], v[30:31]
	s_waitcnt lgkmcnt(4)
	v_pk_add_f32 v[12:13], v[12:13], v[36:37]
	v_pk_add_f32 v[10:11], v[10:11], v[34:35]
	s_waitcnt lgkmcnt(3)
	v_pk_add_f32 v[12:13], v[12:13], v[40:41]
	v_pk_add_f32 v[10:11], v[10:11], v[38:39]
	s_waitcnt lgkmcnt(2)
	v_pk_add_f32 v[12:13], v[12:13], v[44:45]
	v_pk_add_f32 v[10:11], v[10:11], v[42:43]
	s_waitcnt lgkmcnt(1)
	v_pk_add_f32 v[12:13], v[12:13], v[48:49]
	v_pk_add_f32 v[10:11], v[10:11], v[46:47]
	v_lshl_add_u64 v[54:55], s[6:7], 0, v[0:1]
	s_waitcnt lgkmcnt(0)
	v_pk_add_f32 v[12:13], v[12:13], v[52:53]
	v_pk_add_f32 v[10:11], v[10:11], v[50:51]
	s_waitcnt vmcnt(0)
	v_pk_add_f32 v[8:9], v[12:13], v[8:9]
	v_pk_add_f32 v[6:7], v[10:11], v[6:7]
	v_lshl_add_u64 v[10:11], v[54:55], 0, v[14:15]
	global_store_dwordx4 v[10:11], v[6:9], off
	s_branch .LBB0_871
